# rg_scan2 carry-fold loops: next 3 carry chunks' loads kept in flight (4 rotating VGPR sets) instead of one memory round trip per chunk
# speedup vs baseline: 1.0232x; 1.0031x over previous
; __device__ __forceinline__ void rg_fold8(const float* CAR, int b, int d, int ncar, int cg, float* h) {
; #pragma unroll
;     for (int e = 0; e < 8; ++e) h[e] = 0.f;
;     for (int c = 0; c < ncar; ++c) { const float* cp = CAR + ((size_t)((b * 2 + d) * 72 + c) * 160 + cg) * 16; const f32x4 p0 = *(const f32x4*)cp, p1 = *(const f32x4*)(cp + 4), s0 = *(const f32x4*)(cp + 8), s1 = *(const f32x4*)(cp + 12);
; #pragma unroll
;         for (int e = 0; e < 4; ++e) { h[e] = p0[e] * h[e] + s0[e]; h[4 + e] = p1[e] * h[4 + e] + s1[e]; } }
; }
; __device__ __forceinline__ void rg_scan2_phase(const bf16_t* RA0, bf16_t* RI0, const bf16_t* RA1, const bf16_t* RI1, const bf16_t* XCV, const float* bap, const float* bxp, const float* lamp, const float* CAR, bf16_t* Gb, int gtid, int ngt) {
;     for (int it = gtid; it < NB * 36 * 160; it += ngt) { const int cg = it % 160, tc = (it / 160) % 36, b = it / (160 * 36);
;         const int row0 = tc < 4 ? ML + b * CTX + 64 * tc : b * SEQ + 64 * (tc - 4);
;         const int cbk = tc < 4 ? 3 - tc : 4 + (35 - tc);
;         float h[8], ba[8], bx[8], sp[8];
;         rg_fold8(CAR, b, 0, 2 * tc, cg, h); rg_consts8(bap, bxp, lamp, 8 * cg, ba, bx, sp);
.LBB0_1209:
	v_mul_hi_i32 v0, v72, s43
	v_lshrrev_b32_e32 v1, 31, v0
	v_ashrrev_i32_e32 v0, 6, v0
	v_add_u32_e32 v0, v0, v1
	v_mul_hi_i32 v1, v0, s49
	v_lshrrev_b32_e32 v2, 31, v1
	v_ashrrev_i32_e32 v1, 3, v1
	v_add_u32_e32 v1, v1, v2
	v_mul_lo_u32 v1, v1, 36
	v_sub_u32_e32 v64, v0, v1
	v_mul_hi_i32 v1, v72, s44
	v_add_u32_e32 v1, v1, v72
	v_lshrrev_b32_e32 v2, 31, v1
	v_ashrrev_i32_e32 v1, 12, v1
	v_add_u32_e32 v65, v1, v2
	v_cmp_lt_i32_e32 vcc, 3, v64
	v_lshlrev_b32_e32 v1, 6, v64
	s_and_saveexec_b64 s[2:3], vcc
	s_xor_b64 s[6:7], exec, s[2:3]
	v_lshlrev_b32_e32 v2, 11, v65
	s_movk_i32 s1, 0xff00
	v_add3_u32 v22, v2, v1, s1
	s_or_saveexec_b64 s[6:7], s[6:7]
	v_mov_b32_e32 v66, 39
	s_xor_b64 exec, exec, s[6:7]
	v_lshlrev_b32_e32 v2, 8, v65
	v_add3_u32 v22, v2, v1, s40
	v_mov_b32_e32 v66, 3
	s_or_b64 exec, exec, s[6:7]
	v_mul_lo_u32 v0, v0, s41
	v_sub_u32_e32 v28, v72, v0
	v_cmp_lt_i32_e32 vcc, 0, v64
	v_mov_b32_e32 v58, 0
	v_ashrrev_i32_e32 v29, 31, v28
	v_mov_b32_e32 v52, 0
	v_mov_b32_e32 v46, 0
	v_mov_b32_e32 v48, 0
	v_mov_b32_e32 v50, 0
	v_mov_b32_e32 v44, 0
	v_mov_b32_e32 v42, 0
	v_mov_b32_e32 v40, 0
	s_and_saveexec_b64 s[6:7], vcc
	s_cbranch_execz .LBB0_1217
	v_mul_i32_i24_e32 v3, 0x90, v65
	v_lshlrev_b64 v[0:1], 6, v[28:29]
	s_movk_i32 s1, 0x2800
	v_mad_i64_i32 v[0:1], s[2:3], v3, s1, v[0:1]
	v_mov_b32_e32 v40, 0
	v_lshlrev_b32_e32 v2, 1, v64
	v_lshl_add_u64 v[0:1], s[20:21], 0, v[0:1]
	s_mov_b64 s[24:25], 0
	v_mov_b32_e32 v41, v40
	v_mov_b32_e32 v44, v40
	v_mov_b32_e32 v45, v40
	v_mov_b32_e32 v48, v40
	v_mov_b32_e32 v49, v40
	v_mov_b32_e32 v52, v40
	v_mov_b32_e32 v53, v40
	s_mov_b64 s[2:3], 0x2800
	global_load_dwordx4 v[96:99], v[0:1], off offset:48
	global_load_dwordx4 v[100:103], v[0:1], off offset:32
	global_load_dwordx4 v[104:107], v[0:1], off
	global_load_dwordx4 v[108:111], v[0:1], off offset:16
	v_lshl_add_u64 v[0:1], v[0:1], 0, s[2:3]
	global_load_dwordx4 v[112:115], v[0:1], off offset:48
	global_load_dwordx4 v[116:119], v[0:1], off offset:32
	global_load_dwordx4 v[120:123], v[0:1], off
	global_load_dwordx4 v[124:127], v[0:1], off offset:16
	v_lshl_add_u64 v[0:1], v[0:1], 0, s[2:3]
	global_load_dwordx4 v[128:131], v[0:1], off offset:48
	global_load_dwordx4 v[132:135], v[0:1], off offset:32
	global_load_dwordx4 v[136:139], v[0:1], off
	global_load_dwordx4 v[140:143], v[0:1], off offset:16
	v_lshl_add_u64 v[0:1], v[0:1], 0, s[2:3]
.LBB0_1215:
	global_load_dwordx4 v[144:147], v[0:1], off offset:48
	global_load_dwordx4 v[148:151], v[0:1], off offset:32
	global_load_dwordx4 v[152:155], v[0:1], off
	global_load_dwordx4 v[156:159], v[0:1], off offset:16
	v_add_u32_e32 v2, -1, v2
	v_cmp_eq_u32_e32 vcc, 0, v2
	v_lshl_add_u64 v[0:1], v[0:1], 0, s[2:3]
	s_or_b64 s[24:25], vcc, s[24:25]
	s_waitcnt vmcnt(12)
	v_pk_fma_f32 v[40:41], v[40:41], v[104:105], v[100:101]
	v_pk_fma_f32 v[48:49], v[48:49], v[108:109], v[96:97]
	v_pk_fma_f32 v[44:45], v[44:45], v[106:107], v[102:103]
	v_pk_fma_f32 v[52:53], v[52:53], v[110:111], v[98:99]
	s_andn2_b64 exec, exec, s[24:25]
	s_cbranch_execz .Lfold1_done
	global_load_dwordx4 v[96:99], v[0:1], off offset:48
	global_load_dwordx4 v[100:103], v[0:1], off offset:32
	global_load_dwordx4 v[104:107], v[0:1], off
	global_load_dwordx4 v[108:111], v[0:1], off offset:16
	v_add_u32_e32 v2, -1, v2
	v_cmp_eq_u32_e32 vcc, 0, v2
	v_lshl_add_u64 v[0:1], v[0:1], 0, s[2:3]
	s_or_b64 s[24:25], vcc, s[24:25]
	s_waitcnt vmcnt(12)
	v_pk_fma_f32 v[40:41], v[40:41], v[120:121], v[116:117]
	v_pk_fma_f32 v[48:49], v[48:49], v[124:125], v[112:113]
	v_pk_fma_f32 v[44:45], v[44:45], v[122:123], v[118:119]
	v_pk_fma_f32 v[52:53], v[52:53], v[126:127], v[114:115]
	s_andn2_b64 exec, exec, s[24:25]
	s_cbranch_execz .Lfold1_done
	global_load_dwordx4 v[112:115], v[0:1], off offset:48
	global_load_dwordx4 v[116:119], v[0:1], off offset:32
	global_load_dwordx4 v[120:123], v[0:1], off
	global_load_dwordx4 v[124:127], v[0:1], off offset:16
	v_add_u32_e32 v2, -1, v2
	v_cmp_eq_u32_e32 vcc, 0, v2
	v_lshl_add_u64 v[0:1], v[0:1], 0, s[2:3]
	s_or_b64 s[24:25], vcc, s[24:25]
	s_waitcnt vmcnt(12)
	v_pk_fma_f32 v[40:41], v[40:41], v[136:137], v[132:133]
	v_pk_fma_f32 v[48:49], v[48:49], v[140:141], v[128:129]
	v_pk_fma_f32 v[44:45], v[44:45], v[138:139], v[134:135]
	v_pk_fma_f32 v[52:53], v[52:53], v[142:143], v[130:131]
	s_andn2_b64 exec, exec, s[24:25]
	s_cbranch_execz .Lfold1_done
	global_load_dwordx4 v[128:131], v[0:1], off offset:48
	global_load_dwordx4 v[132:135], v[0:1], off offset:32
	global_load_dwordx4 v[136:139], v[0:1], off
	global_load_dwordx4 v[140:143], v[0:1], off offset:16
	v_add_u32_e32 v2, -1, v2
	v_cmp_eq_u32_e32 vcc, 0, v2
	v_lshl_add_u64 v[0:1], v[0:1], 0, s[2:3]
	s_or_b64 s[24:25], vcc, s[24:25]
	s_waitcnt vmcnt(12)
	v_pk_fma_f32 v[40:41], v[40:41], v[152:153], v[148:149]
	v_pk_fma_f32 v[48:49], v[48:49], v[156:157], v[144:145]
	v_pk_fma_f32 v[44:45], v[44:45], v[154:155], v[150:151]
	v_pk_fma_f32 v[52:53], v[52:53], v[158:159], v[146:147]
	s_andn2_b64 exec, exec, s[24:25]
	s_cbranch_execnz .LBB0_1215
.Lfold1_done:
	s_or_b64 exec, exec, s[24:25]
	v_mov_b32_e32 v58, v53
	v_mov_b32_e32 v46, v49
	v_mov_b32_e32 v50, v45
	v_mov_b32_e32 v42, v41

; __device__ __forceinline__ void rg_fold8(const float* CAR, int b, int d, int ncar, int cg, float* h) {
; #pragma unroll
;     for (int e = 0; e < 8; ++e) h[e] = 0.f;
;     for (int c = 0; c < ncar; ++c) { const float* cp = CAR + ((size_t)((b * 2 + d) * 72 + c) * 160 + cg) * 16; const f32x4 p0 = *(const f32x4*)cp, p1 = *(const f32x4*)(cp + 4), s0 = *(const f32x4*)(cp + 8), s1 = *(const f32x4*)(cp + 12);
; #pragma unroll
;         for (int e = 0; e < 4; ++e) { h[e] = p0[e] * h[e] + s0[e]; h[4 + e] = p1[e] * h[4 + e] + s1[e]; } }
; }
; __device__ __forceinline__ void rg_scan2_phase(const bf16_t* RA0, bf16_t* RI0, const bf16_t* RA1, const bf16_t* RI1, const bf16_t* XCV, const float* bap, const float* bxp, const float* lamp, const float* CAR, bf16_t* Gb, int gtid, int ngt) {
;     ...
;         rg_fold8(CAR, b, 1, 2 * cbk, cg, h); rg_consts8(bap, bxp, lamp, 1280 + 8 * cg, ba, bx, sp);
.LBB0_1379:
	v_cmp_ne_u32_e32 vcc, v66, v64
	v_mov_b32_e32 v50, 0
	v_mov_b32_e32 v58, 0
	v_mov_b32_e32 v60, 0
	v_mov_b32_e32 v54, 0
	v_mov_b32_e32 v56, 0
	v_mov_b32_e32 v48, 0
	v_mov_b32_e32 v52, 0
	v_mov_b32_e32 v46, 0
	s_and_saveexec_b64 s[6:7], vcc
	s_cbranch_execz .LBB0_1383
	v_sub_u32_e32 v0, v66, v64
	s_movk_i32 s1, 0x90
	v_mov_b32_e32 v1, 0x48
	v_mov_b32_e32 v46, 0
	v_lshlrev_b32_e32 v0, 1, v0
	v_mad_i32_i24 v1, v65, s1, v1
	s_mov_b64 s[24:25], 0
	v_mov_b32_e32 v47, v46
	v_mov_b32_e32 v48, v46
	v_mov_b32_e32 v49, v46
	v_mov_b32_e32 v54, v46
	v_mov_b32_e32 v55, v46
	v_mov_b32_e32 v58, v46
	v_mov_b32_e32 v59, v46
	v_mad_i64_i32 v[160:161], s[2:3], v1, s41, v[28:29]
	v_lshlrev_b64 v[160:161], 6, v[160:161]
	v_lshl_add_u64 v[160:161], s[20:21], 0, v[160:161]
	global_load_dwordx4 v[96:99], v[160:161], off offset:48
	global_load_dwordx4 v[100:103], v[160:161], off offset:32
	global_load_dwordx4 v[104:107], v[160:161], off
	global_load_dwordx4 v[108:111], v[160:161], off offset:16
	v_add_u32_e32 v1, 1, v1
	v_mad_i64_i32 v[160:161], s[2:3], v1, s41, v[28:29]
	v_lshlrev_b64 v[160:161], 6, v[160:161]
	v_lshl_add_u64 v[160:161], s[20:21], 0, v[160:161]
	global_load_dwordx4 v[112:115], v[160:161], off offset:48
	global_load_dwordx4 v[116:119], v[160:161], off offset:32
	global_load_dwordx4 v[120:123], v[160:161], off
	global_load_dwordx4 v[124:127], v[160:161], off offset:16
	v_add_u32_e32 v1, 1, v1
	v_mad_i64_i32 v[160:161], s[2:3], v1, s41, v[28:29]
	v_lshlrev_b64 v[160:161], 6, v[160:161]
	v_lshl_add_u64 v[160:161], s[20:21], 0, v[160:161]
	global_load_dwordx4 v[128:131], v[160:161], off offset:48
	global_load_dwordx4 v[132:135], v[160:161], off offset:32
	global_load_dwordx4 v[136:139], v[160:161], off
	global_load_dwordx4 v[140:143], v[160:161], off offset:16
	v_add_u32_e32 v1, 1, v1
.LBB0_1381:
	v_mad_i64_i32 v[160:161], s[2:3], v1, s41, v[28:29]
	v_lshlrev_b64 v[160:161], 6, v[160:161]
	v_lshl_add_u64 v[160:161], s[20:21], 0, v[160:161]
	global_load_dwordx4 v[144:147], v[160:161], off offset:48
	global_load_dwordx4 v[148:151], v[160:161], off offset:32
	global_load_dwordx4 v[152:155], v[160:161], off
	global_load_dwordx4 v[156:159], v[160:161], off offset:16
	v_add_u32_e32 v1, 1, v1
	v_add_u32_e32 v0, -1, v0
	v_cmp_eq_u32_e32 vcc, 0, v0
	s_nop 0
	s_or_b64 s[24:25], vcc, s[24:25]
	s_waitcnt vmcnt(12)
	v_pk_fma_f32 v[46:47], v[46:47], v[104:105], v[100:101]
	v_pk_fma_f32 v[54:55], v[54:55], v[108:109], v[96:97]
	v_pk_fma_f32 v[48:49], v[48:49], v[106:107], v[102:103]
	v_pk_fma_f32 v[58:59], v[58:59], v[110:111], v[98:99]
	s_andn2_b64 exec, exec, s[24:25]
	s_cbranch_execz .Lfold2_done
	v_mad_i64_i32 v[160:161], s[2:3], v1, s41, v[28:29]
	v_lshlrev_b64 v[160:161], 6, v[160:161]
	v_lshl_add_u64 v[160:161], s[20:21], 0, v[160:161]
	global_load_dwordx4 v[96:99], v[160:161], off offset:48
	global_load_dwordx4 v[100:103], v[160:161], off offset:32
	global_load_dwordx4 v[104:107], v[160:161], off
	global_load_dwordx4 v[108:111], v[160:161], off offset:16
	v_add_u32_e32 v1, 1, v1
	v_add_u32_e32 v0, -1, v0
	v_cmp_eq_u32_e32 vcc, 0, v0
	s_nop 0
	s_or_b64 s[24:25], vcc, s[24:25]
	s_waitcnt vmcnt(12)
	v_pk_fma_f32 v[46:47], v[46:47], v[120:121], v[116:117]
	v_pk_fma_f32 v[54:55], v[54:55], v[124:125], v[112:113]
	v_pk_fma_f32 v[48:49], v[48:49], v[122:123], v[118:119]
	v_pk_fma_f32 v[58:59], v[58:59], v[126:127], v[114:115]
	s_andn2_b64 exec, exec, s[24:25]
	s_cbranch_execz .Lfold2_done
	v_mad_i64_i32 v[160:161], s[2:3], v1, s41, v[28:29]
	v_lshlrev_b64 v[160:161], 6, v[160:161]
	v_lshl_add_u64 v[160:161], s[20:21], 0, v[160:161]
	global_load_dwordx4 v[112:115], v[160:161], off offset:48
	global_load_dwordx4 v[116:119], v[160:161], off offset:32
	global_load_dwordx4 v[120:123], v[160:161], off
	global_load_dwordx4 v[124:127], v[160:161], off offset:16
	v_add_u32_e32 v1, 1, v1
	v_add_u32_e32 v0, -1, v0
	v_cmp_eq_u32_e32 vcc, 0, v0
	s_nop 0
	s_or_b64 s[24:25], vcc, s[24:25]
	s_waitcnt vmcnt(12)
	v_pk_fma_f32 v[46:47], v[46:47], v[136:137], v[132:133]
	v_pk_fma_f32 v[54:55], v[54:55], v[140:141], v[128:129]
	v_pk_fma_f32 v[48:49], v[48:49], v[138:139], v[134:135]
	v_pk_fma_f32 v[58:59], v[58:59], v[142:143], v[130:131]
	s_andn2_b64 exec, exec, s[24:25]
	s_cbranch_execz .Lfold2_done
	v_mad_i64_i32 v[160:161], s[2:3], v1, s41, v[28:29]
	v_lshlrev_b64 v[160:161], 6, v[160:161]
	v_lshl_add_u64 v[160:161], s[20:21], 0, v[160:161]
	global_load_dwordx4 v[128:131], v[160:161], off offset:48
	global_load_dwordx4 v[132:135], v[160:161], off offset:32
	global_load_dwordx4 v[136:139], v[160:161], off
	global_load_dwordx4 v[140:143], v[160:161], off offset:16
	v_add_u32_e32 v1, 1, v1
	v_add_u32_e32 v0, -1, v0
	v_cmp_eq_u32_e32 vcc, 0, v0
	s_nop 0
	s_or_b64 s[24:25], vcc, s[24:25]
	s_waitcnt vmcnt(12)
	v_pk_fma_f32 v[46:47], v[46:47], v[152:153], v[148:149]
	v_pk_fma_f32 v[54:55], v[54:55], v[156:157], v[144:145]
	v_pk_fma_f32 v[48:49], v[48:49], v[154:155], v[150:151]
	v_pk_fma_f32 v[58:59], v[58:59], v[158:159], v[146:147]
	s_andn2_b64 exec, exec, s[24:25]
	s_cbranch_execnz .LBB0_1381
.Lfold2_done:
	s_or_b64 exec, exec, s[24:25]
	v_mov_b32_e32 v50, v59
	v_mov_b32_e32 v60, v55
	v_mov_b32_e32 v56, v49
	v_mov_b32_e32 v52, v47
